# steady attention step: the three tile DMAs spread over the step (K behind PV1, V half 1 behind PV6, V half 2 behind PV10)
# baseline (speedup 1.0000x reference)
.LBB0_973:
	s_lshl_b32 s40, s2, 1
	v_add_u32_e32 v216, s40, v242
	ds_read_b64_tr_b16 v[210:211], v216 offset:24576
	ds_read_b64_tr_b16 v[212:213], v216 offset:25088
	v_mfma_f32_32x32x16_bf16 v[130:145], v[206:209], v[174:177], v[66:81]
	v_add_f32_e32 v114, v98, v99
	v_add_f32_e32 v114, v100, v114
	v_add_f32_e32 v114, v101, v114
	v_add_f32_e32 v114, v102, v114
	v_add_f32_e32 v114, v103, v114
	v_cvt_pk_bf16_f32 v158, v98, v99
	v_cvt_pk_bf16_f32 v159, v100, v101
	ds_read_b64_tr_b16 v[206:207], v216 offset:28672
	ds_read_b64_tr_b16 v[208:209], v216 offset:29184
	v_add_f32_e32 v98, v104, v114
	v_mfma_f32_32x32x16_bf16 v[114:129], v[202:205], v[174:177], v[66:81]
	v_add_f32_e32 v98, v105, v98
	v_add_f32_e32 v98, v106, v98
	v_add_f32_e32 v146, v107, v98
	v_cvt_pk_bf16_f32 v160, v102, v103
	v_cvt_pk_bf16_f32 v161, v104, v105
	ds_read_b64_tr_b16 v[98:99], v216 offset:25600
	ds_read_b64_tr_b16 v[100:101], v216 offset:26112
	v_mfma_f32_32x32x16_bf16 v[130:145], v[198:201], v[170:173], v[130:145]
	v_add_f32_e32 v102, v108, v146
	v_add_f32_e32 v102, v109, v102
	v_add_f32_e32 v102, v110, v102
	v_add_f32_e32 v146, v111, v102
	v_cvt_pk_bf16_f32 v154, v106, v107
	v_cvt_pk_bf16_f32 v155, v108, v109
	ds_read_b64_tr_b16 v[102:103], v216 offset:29696
	ds_read_b64_tr_b16 v[104:105], v216 offset:30208
	v_mfma_f32_32x32x16_bf16 v[114:129], v[194:197], v[170:173], v[114:129]
	v_add_f32_e32 v106, v112, v146
	v_add_f32_e32 v106, v113, v106
	v_add_f32_e32 v106, v82, v106
	v_add_f32_e32 v146, v83, v106
	v_cvt_pk_bf16_f32 v156, v110, v111
	v_cvt_pk_bf16_f32 v157, v112, v113
	ds_read_b64_tr_b16 v[106:107], v216 offset:26624
	ds_read_b64_tr_b16 v[108:109], v216 offset:27136
	v_mfma_f32_32x32x16_bf16 v[130:145], v[190:193], v[166:169], v[130:145]
	v_add_f32_e32 v110, v84, v146
	v_add_f32_e32 v110, v85, v110
	v_add_f32_e32 v110, v86, v110
	v_add_f32_e32 v146, v87, v110
	v_cvt_pk_bf16_f32 v150, v82, v83
	v_cvt_pk_bf16_f32 v151, v84, v85
	ds_read_b64_tr_b16 v[110:111], v216 offset:30720
	ds_read_b64_tr_b16 v[112:113], v216 offset:31232
	v_mfma_f32_32x32x16_bf16 v[114:129], v[186:189], v[166:169], v[114:129]
	v_add_f32_e32 v82, v88, v146
	v_add_f32_e32 v82, v89, v82
	v_add_f32_e32 v82, v90, v82
	v_add_f32_e32 v82, v91, v82
	v_cvt_pk_bf16_f32 v152, v86, v87
	v_cvt_pk_bf16_f32 v153, v88, v89
	ds_read_b64_tr_b16 v[86:87], v216 offset:27648
	ds_read_b64_tr_b16 v[88:89], v216 offset:28160
	v_mfma_f32_32x32x16_bf16 v[130:145], v[182:185], v[162:165], v[130:145]
	v_add_f32_e32 v82, v92, v82
	v_add_f32_e32 v82, v93, v82
	v_add_f32_e32 v82, v94, v82
	v_add_f32_e32 v82, v95, v82
	v_cvt_pk_bf16_f32 v146, v90, v91
	v_cvt_pk_bf16_f32 v147, v92, v93
	ds_read_b64_tr_b16 v[90:91], v216 offset:31744
	ds_read_b64_tr_b16 v[92:93], v216 offset:32256
	v_mfma_f32_32x32x16_bf16 v[114:129], v[178:181], v[162:165], v[114:129]
	v_add_f32_e32 v82, v96, v82
	v_add_f32_e32 v82, v97, v82
	v_add_f32_e32 v230, v244, v82
	v_cvt_pk_bf16_f32 v148, v94, v95
	v_cvt_pk_bf16_f32 v149, v96, v97
	s_waitcnt lgkmcnt(8)
	v_mfma_f32_32x32x16_bf16 v[50:65], v[158:161], v[210:213], v[50:65]
	s_add_i32 m0, s46, s83
	s_lshl_b32 s2, s44, 1
	global_load_lds_dwordx4 v218, s[98:99]
	s_add_u32 s98, s98, 0x10000
	s_addc_u32 s99, s99, 0
	v_mfma_f32_32x32x16_bf16 v[34:49], v[158:161], v[206:209], v[34:49]
	v_mfma_f32_32x32x16_bf16 v[50:65], v[154:157], v[98:101], v[50:65]
	v_max_f32_e32 v82, v130, v131
	v_max3_f32 v83, v132, v133, v115
	v_max3_f32 v82, v82, v114, v116
	v_max3_f32 v82, v82, v117, v134
	v_max3_f32 v83, v83, v136, v137
	v_max3_f32 v82, v82, v135, v118
	v_max3_f32 v83, v83, v120, v121
	v_max3_f32 v82, v82, v119, v138
	v_mfma_f32_32x32x16_bf16 v[34:49], v[154:157], v[102:105], v[34:49]
	v_max3_f32 v83, v83, v140, v141
	v_max3_f32 v82, v82, v139, v122
	v_max3_f32 v83, v83, v124, v125
	v_max3_f32 v82, v82, v123, v142
	v_max3_f32 v83, v83, v144, v145
	v_max3_f32 v82, v82, v143, v126
	v_max3_f32 v83, v83, v128, v129
	v_max3_f32 v82, v82, v127, v83
	v_mov_b32_e32 v83, v82
	v_add_u32_e32 v94, s44, v241
	v_add_u32_e32 v102, s40, v228
	v_permlane32_swap_b32_e32 v82, v83
	v_max_f32_e32 v82, v82, v83
	v_cmp_lt_f32_e32 vcc, s87, v82
	s_cbranch_vccnz .LBB0_981
.LBB0_974:
	ds_read_b128 v[82:85], v94
	ds_read_b128 v[198:201], v94 offset:512
	ds_read_b128 v[202:205], v94 offset:2048
	ds_read_b128 v[194:197], v94 offset:2560
	s_waitcnt lgkmcnt(4)
	v_mfma_f32_32x32x16_bf16 v[50:65], v[150:153], v[106:109], v[50:65]
	v_exp_f32_e32 v130, v130
	v_exp_f32_e32 v131, v131
	v_exp_f32_e32 v132, v132
	ds_read_b128 v[190:193], v94 offset:4096
	ds_read_b128 v[186:189], v94 offset:4608
	ds_read_b128 v[182:185], v94 offset:6144
	ds_read_b128 v[178:181], v94 offset:6656
	ds_read_b64_tr_b16 v[98:99],v102 offset:3072
	ds_read_b64_tr_b16 v[100:101],v102 offset:3584
	ds_read_b64_tr_b16 v[94:95],v102 offset:2048
	ds_read_b64_tr_b16 v[96:97],v102 offset:2560
	v_mfma_f32_32x32x16_bf16 v[34:49], v[150:153], v[110:113], v[34:49]
	s_add_i32 m0, s2, s84
	v_exp_f32_e32 v133, v133
	v_exp_f32_e32 v134, v134
	v_exp_f32_e32 v135, v135
	global_load_lds_dwordx4 v219, s[100:101]
	v_mfma_f32_32x32x16_bf16 v[50:65], v[146:149], v[86:89], v[50:65]
	v_exp_f32_e32 v136, v136
	v_exp_f32_e32 v137, v137
	v_exp_f32_e32 v138, v138
	ds_read_b64_tr_b16 v[86:87],v102 offset:0
	ds_read_b64_tr_b16 v[88:89],v102 offset:512
	v_mfma_f32_32x32x16_bf16 v[34:49], v[146:149], v[90:93], v[34:49]
	v_exp_f32_e32 v139, v139
	v_exp_f32_e32 v140, v140
	v_exp_f32_e32 v141, v141
	ds_read_b64_tr_b16 v[90:91],v102 offset:1024
	ds_read_b64_tr_b16 v[92:93],v102 offset:1536
	s_waitcnt lgkmcnt(6)
	v_mfma_f32_32x32x16_bf16 v[18:33], v[146:149], v[98:101], v[18:33]
	v_exp_f32_e32 v142, v142
	v_exp_f32_e32 v143, v143
	v_exp_f32_e32 v144, v144
	ds_read_b64_tr_b16 v[98:99],v102 offset:7168
	ds_read_b64_tr_b16 v[100:101],v102 offset:7680
	s_waitcnt lgkmcnt(6)
	v_mfma_f32_32x32x16_bf16 v[18:33], v[150:153], v[94:97], v[18:33]
	s_addk_i32 m0, 0x1f80
	v_exp_f32_e32 v145, v145
	v_exp_f32_e32 v114, v114
	v_exp_f32_e32 v115, v115
	ds_read_b64_tr_b16 v[94:95],v102 offset:6144
	ds_read_b64_tr_b16 v[96:97],v102 offset:6656
	global_load_lds_dwordx4 v219, s[100:101] offset:128
	s_add_u32 s100, s100, 0x10000
	s_addc_u32 s101, s101, 0
	s_waitcnt lgkmcnt(6)
	v_mfma_f32_32x32x16_bf16 v[18:33], v[158:161], v[86:89], v[18:33]
	v_exp_f32_e32 v116, v116
	v_exp_f32_e32 v117, v117
	v_exp_f32_e32 v118, v118
	ds_read_b64_tr_b16 v[86:87],v102 offset:4096
	ds_read_b64_tr_b16 v[88:89],v102 offset:4608
	s_waitcnt lgkmcnt(6)
	v_mfma_f32_32x32x16_bf16 v[18:33], v[154:157], v[90:93], v[18:33]
	v_exp_f32_e32 v119, v119
	v_exp_f32_e32 v120, v120
	v_exp_f32_e32 v121, v121
	ds_read_b64_tr_b16 v[90:91],v102 offset:5120
	ds_read_b64_tr_b16 v[92:93],v102 offset:5632
	s_waitcnt lgkmcnt(6)
	v_mfma_f32_32x32x16_bf16 v[2:17], v[146:149], v[98:101], v[2:17]
	v_exp_f32_e32 v122, v122
	v_exp_f32_e32 v123, v123
	s_waitcnt vmcnt(3) lgkmcnt(0)
	s_barrier
	v_mfma_f32_32x32x16_bf16 v[2:17], v[150:153], v[94:97], v[2:17]
	v_exp_f32_e32 v124, v124
	v_exp_f32_e32 v125, v125
	v_mfma_f32_32x32x16_bf16 v[2:17], v[158:161], v[86:89], v[2:17]
	v_exp_f32_e32 v126, v126
	v_exp_f32_e32 v127, v127
	v_mfma_f32_32x32x16_bf16 v[2:17], v[154:157], v[90:93], v[2:17]
	v_exp_f32_e32 v128, v128
	v_exp_f32_e32 v129, v129
	s_cmp_eq_u32 s3, 0
	s_cbranch_scc1 .LBB0_976
	s_waitcnt lgkmcnt(0)
	s_mov_b32 s3, 0
	v_add_u32_e32 v229, s94, v243
	ds_read_b128 v[86:89], v229 offset:96
	ds_read_b128 v[90:93], v229 offset:64
	ds_read_b128 v[94:97], v229 offset:32
	ds_read_b128 v[98:101], v229
	s_waitcnt lgkmcnt(3)
	v_pk_mul_f32 v[62:63], v[62:63], v[86:87]
	s_waitcnt lgkmcnt(2)
	v_pk_mul_f32 v[58:59], v[58:59], v[90:91]
	s_waitcnt lgkmcnt(1)
	v_pk_mul_f32 v[54:55], v[54:55], v[94:95]
	v_pk_mul_f32 v[64:65], v[64:65], v[88:89]
	v_pk_mul_f32 v[60:61], v[60:61], v[92:93]
	v_pk_mul_f32 v[56:57], v[56:57], v[96:97]
	s_waitcnt lgkmcnt(0)
	v_pk_mul_f32 v[52:53], v[52:53], v[100:101]
	v_pk_mul_f32 v[50:51], v[50:51], v[98:99]
	v_pk_mul_f32 v[46:47], v[46:47], v[86:87]
	v_pk_mul_f32 v[42:43], v[42:43], v[90:91]
	v_pk_mul_f32 v[38:39], v[38:39], v[94:95]
	v_pk_mul_f32 v[48:49], v[48:49], v[88:89]
	v_pk_mul_f32 v[44:45], v[44:45], v[92:93]
	v_pk_mul_f32 v[40:41], v[40:41], v[96:97]
	v_pk_mul_f32 v[36:37], v[36:37], v[100:101]
	v_pk_mul_f32 v[34:35], v[34:35], v[98:99]
	v_pk_mul_f32 v[30:31], v[30:31], v[86:87]
	v_pk_mul_f32 v[26:27], v[26:27], v[90:91]
	v_pk_mul_f32 v[22:23], v[22:23], v[94:95]
	v_pk_mul_f32 v[32:33], v[32:33], v[88:89]
	v_pk_mul_f32 v[28:29], v[28:29], v[92:93]
	v_pk_mul_f32 v[24:25], v[24:25], v[96:97]
	v_pk_mul_f32 v[20:21], v[20:21], v[100:101]
	v_pk_mul_f32 v[18:19], v[18:19], v[98:99]
	v_pk_mul_f32 v[14:15], v[14:15], v[86:87]
	v_pk_mul_f32 v[10:11], v[10:11], v[90:91]
	v_pk_mul_f32 v[6:7], v[6:7], v[94:95]
	v_pk_mul_f32 v[16:17], v[16:17], v[88:89]
	v_pk_mul_f32 v[12:13], v[12:13], v[92:93]
	v_pk_mul_f32 v[8:9], v[8:9], v[96:97]
	v_pk_mul_f32 v[4:5], v[4:5], v[100:101]
	v_pk_mul_f32 v[2:3], v[2:3], v[98:99]
.LBB0_976:
	s_add_i32 s2, s44, 0x2000
	s_cmpk_lg_i32 s44, 0x4000
	s_cselect_b32 s40, s2, 0
	s_lshl_b32 s45, s46, 1
	v_add_u32_e32 v231, s45, v242
	ds_read_b64_tr_b16 v[210:211], v231 offset:24576
	ds_read_b64_tr_b16 v[212:213], v231 offset:25088
	v_mfma_f32_32x32x16_bf16 v[98:113], v[82:85], v[174:177], v[66:81]
	v_add_f32_e32 v86, v130, v131
	v_add_f32_e32 v86, v132, v86
	v_add_f32_e32 v86, v133, v86
	v_add_f32_e32 v86, v134, v86
	v_add_f32_e32 v86, v135, v86
	v_cvt_pk_bf16_f32 v158, v130, v131
	v_cvt_pk_bf16_f32 v159, v132, v133
	ds_read_b64_tr_b16 v[206:207], v231 offset:28672
	ds_read_b64_tr_b16 v[208:209], v231 offset:29184
	v_add_f32_e32 v82, v136, v86
	v_add_f32_e32 v82, v137, v82
	v_add_f32_e32 v82, v138, v82
	v_add_f32_e32 v146, v139, v82
	v_mfma_f32_32x32x16_bf16 v[82:97], v[198:201], v[174:177], v[66:81]
	v_cvt_pk_bf16_f32 v160, v134, v135
	v_cvt_pk_bf16_f32 v161, v136, v137
	ds_read_b64_tr_b16 v[130:131], v231 offset:25600
	ds_read_b64_tr_b16 v[132:133], v231 offset:26112
	v_mfma_f32_32x32x16_bf16 v[98:113], v[202:205], v[170:173], v[98:113]
	v_add_f32_e32 v134, v140, v146
	v_add_f32_e32 v134, v141, v134
	v_add_f32_e32 v134, v142, v134
	v_add_f32_e32 v146, v143, v134
	v_cvt_pk_bf16_f32 v154, v138, v139
	v_cvt_pk_bf16_f32 v155, v140, v141
	ds_read_b64_tr_b16 v[134:135], v231 offset:29696
	ds_read_b64_tr_b16 v[136:137], v231 offset:30208
	v_mfma_f32_32x32x16_bf16 v[82:97], v[194:197], v[170:173], v[82:97]
	v_add_f32_e32 v138, v144, v146
	v_add_f32_e32 v138, v145, v138
	v_add_f32_e32 v138, v114, v138
	v_add_f32_e32 v146, v115, v138
	v_cvt_pk_bf16_f32 v156, v142, v143
	v_cvt_pk_bf16_f32 v157, v144, v145
	ds_read_b64_tr_b16 v[138:139], v231 offset:26624
	ds_read_b64_tr_b16 v[140:141], v231 offset:27136
	v_mfma_f32_32x32x16_bf16 v[98:113], v[190:193], v[166:169], v[98:113]
	v_add_f32_e32 v142, v116, v146
	v_add_f32_e32 v142, v117, v142
	v_add_f32_e32 v142, v118, v142
	v_add_f32_e32 v142, v119, v142
	v_cvt_pk_bf16_f32 v150, v114, v115
	v_cvt_pk_bf16_f32 v151, v116, v117
	ds_read_b64_tr_b16 v[114:115], v231 offset:30720
	ds_read_b64_tr_b16 v[116:117], v231 offset:31232
	v_mfma_f32_32x32x16_bf16 v[82:97], v[186:189], v[166:169], v[82:97]
	v_add_f32_e32 v142, v120, v142
	v_add_f32_e32 v142, v121, v142
	v_add_f32_e32 v142, v122, v142
	v_add_f32_e32 v142, v123, v142
	v_cvt_pk_bf16_f32 v152, v118, v119
	v_cvt_pk_bf16_f32 v153, v120, v121
	ds_read_b64_tr_b16 v[118:119], v231 offset:27648
	ds_read_b64_tr_b16 v[120:121], v231 offset:28160
	v_mfma_f32_32x32x16_bf16 v[98:113], v[182:185], v[162:165], v[98:113]
	v_add_f32_e32 v142, v124, v142
	v_add_f32_e32 v142, v125, v142
	v_add_f32_e32 v142, v126, v142
	v_add_f32_e32 v142, v127, v142
	v_cvt_pk_bf16_f32 v146, v122, v123
	v_cvt_pk_bf16_f32 v147, v124, v125
	ds_read_b64_tr_b16 v[122:123], v231 offset:31744
	ds_read_b64_tr_b16 v[124:125], v231 offset:32256
	v_mfma_f32_32x32x16_bf16 v[82:97], v[178:181], v[162:165], v[82:97]
	v_add_f32_e32 v142, v128, v142
	v_add_f32_e32 v142, v129, v142
	v_cvt_pk_bf16_f32 v148, v126, v127
	v_cvt_pk_bf16_f32 v149, v128, v129
	s_waitcnt lgkmcnt(8)
	v_mfma_f32_32x32x16_bf16 v[50:65], v[158:161], v[210:213], v[50:65]
	s_add_i32 m0, s44, s83
	s_lshl_b32 s2, s40, 1
	global_load_lds_dwordx4 v218, s[98:99]
	s_add_u32 s98, s98, 0x10000
	s_addc_u32 s99, s99, 0
	v_mfma_f32_32x32x16_bf16 v[34:49], v[158:161], v[206:209], v[34:49]
	v_mfma_f32_32x32x16_bf16 v[50:65], v[154:157], v[130:133], v[50:65]
	v_max_f32_e32 v126, v98, v99
	v_max3_f32 v127, v100, v101, v83
	v_max3_f32 v126, v126, v82, v84
	v_max3_f32 v126, v126, v85, v102
	v_max3_f32 v127, v127, v104, v105
	v_max3_f32 v126, v126, v103, v86
	v_max3_f32 v127, v127, v88, v89
	v_max3_f32 v126, v126, v87, v106
	v_mfma_f32_32x32x16_bf16 v[34:49], v[154:157], v[134:137], v[34:49]
	v_max3_f32 v127, v127, v108, v109
	v_max3_f32 v126, v126, v107, v90
	v_max3_f32 v127, v127, v92, v93
	v_max3_f32 v126, v126, v91, v110
	v_max3_f32 v127, v127, v112, v113
	v_max3_f32 v126, v126, v111, v94
	v_max3_f32 v127, v127, v96, v97
	v_max3_f32 v126, v126, v95, v127
	v_mov_b32_e32 v127, v126
	v_add_f32_e32 v244, v230, v142
	v_add_u32_e32 v130, s45, v228
	v_permlane32_swap_b32_e32 v126, v127
	v_max_f32_e32 v126, v126, v127
	v_cmp_lt_f32_e32 vcc, s87, v126
	s_cbranch_vccnz .LBB0_984
.LBB0_977:
	v_add_u32_e32 v126, s40, v241
	ds_read_b128 v[206:209], v126
	ds_read_b128 v[202:205], v126 offset:512
	ds_read_b128 v[198:201], v126 offset:2048
	ds_read_b128 v[194:197], v126 offset:2560
	s_waitcnt lgkmcnt(4)
	v_mfma_f32_32x32x16_bf16 v[50:65], v[150:153], v[138:141], v[50:65]
	v_exp_f32_e32 v98, v98
	v_exp_f32_e32 v99, v99
	v_exp_f32_e32 v100, v100
	ds_read_b128 v[190:193], v126 offset:4096
	ds_read_b128 v[186:189], v126 offset:4608
	ds_read_b128 v[182:185], v126 offset:6144
	ds_read_b128 v[178:181], v126 offset:6656
	ds_read_b64_tr_b16 v[126:127],v130 offset:3072
	ds_read_b64_tr_b16 v[128:129],v130 offset:3584
	v_mfma_f32_32x32x16_bf16 v[34:49], v[150:153], v[114:117], v[34:49]
	s_add_i32 s46, s2, s84
	s_mov_b32 m0, s46
	v_exp_f32_e32 v101, v101
	v_exp_f32_e32 v102, v102
	v_exp_f32_e32 v103, v103
	ds_read_b64_tr_b16 v[114:115],v130 offset:0
	ds_read_b64_tr_b16 v[116:117],v130 offset:512
	global_load_lds_dwordx4 v219, s[100:101]
	v_mfma_f32_32x32x16_bf16 v[50:65], v[146:149], v[118:121], v[50:65]
	v_exp_f32_e32 v104, v104
	v_exp_f32_e32 v105, v105
	v_exp_f32_e32 v106, v106
	ds_read_b64_tr_b16 v[118:119],v130 offset:1024
	ds_read_b64_tr_b16 v[120:121],v130 offset:1536
	v_mfma_f32_32x32x16_bf16 v[34:49], v[146:149], v[122:125], v[34:49]
	v_exp_f32_e32 v107, v107
	v_exp_f32_e32 v108, v108
	v_exp_f32_e32 v109, v109
	ds_read_b64_tr_b16 v[122:123],v130 offset:2048
	ds_read_b64_tr_b16 v[124:125],v130 offset:2560
	s_waitcnt lgkmcnt(6)
	v_mfma_f32_32x32x16_bf16 v[18:33], v[146:149], v[126:129], v[18:33]
	v_exp_f32_e32 v110, v110
	v_exp_f32_e32 v111, v111
	v_exp_f32_e32 v112, v112
	ds_read_b64_tr_b16 v[126:127],v130 offset:7168
	ds_read_b64_tr_b16 v[128:129],v130 offset:7680
	s_waitcnt lgkmcnt(6)
	v_mfma_f32_32x32x16_bf16 v[18:33], v[158:161], v[114:117], v[18:33]
	s_add_i32 m0, s46, 0x1f80
	v_exp_f32_e32 v113, v113
	v_exp_f32_e32 v82, v82
	v_exp_f32_e32 v83, v83
	ds_read_b64_tr_b16 v[114:115],v130 offset:4096
	ds_read_b64_tr_b16 v[116:117],v130 offset:4608
	global_load_lds_dwordx4 v219, s[100:101] offset:128
	s_add_u32 s100, s100, 0x10000
	s_addc_u32 s101, s101, 0
	s_waitcnt lgkmcnt(6)
	v_mfma_f32_32x32x16_bf16 v[18:33], v[154:157], v[118:121], v[18:33]
	v_exp_f32_e32 v84, v84
	v_exp_f32_e32 v85, v85
	v_exp_f32_e32 v86, v86
	ds_read_b64_tr_b16 v[118:119],v130 offset:5120
	ds_read_b64_tr_b16 v[120:121],v130 offset:5632
	s_waitcnt lgkmcnt(6)
	v_mfma_f32_32x32x16_bf16 v[18:33], v[150:153], v[122:125], v[18:33]
	v_exp_f32_e32 v87, v87
	v_exp_f32_e32 v88, v88
	v_exp_f32_e32 v89, v89
	ds_read_b64_tr_b16 v[122:123],v130 offset:6144
	ds_read_b64_tr_b16 v[124:125],v130 offset:6656
	s_waitcnt lgkmcnt(6)
	v_mfma_f32_32x32x16_bf16 v[2:17], v[146:149], v[126:129], v[2:17]
	v_exp_f32_e32 v90, v90
	v_exp_f32_e32 v91, v91
	s_waitcnt vmcnt(3) lgkmcnt(0)
	s_barrier
	v_mfma_f32_32x32x16_bf16 v[2:17], v[158:161], v[114:117], v[2:17]
	v_exp_f32_e32 v92, v92
	v_exp_f32_e32 v93, v93
	v_mfma_f32_32x32x16_bf16 v[2:17], v[154:157], v[118:121], v[2:17]
	v_exp_f32_e32 v94, v94
	v_exp_f32_e32 v95, v95
	v_mfma_f32_32x32x16_bf16 v[2:17], v[150:153], v[122:125], v[2:17]
	v_exp_f32_e32 v96, v96
	v_exp_f32_e32 v97, v97
	s_cmp_eq_u32 s3, 0
	s_cbranch_scc1 .LBB0_979
	s_waitcnt lgkmcnt(0)
	s_mov_b32 s3, 0
	v_add_u32_e32 v229, s94, v243
	ds_read_b128 v[114:117], v229 offset:96
	ds_read_b128 v[118:121], v229 offset:64
	ds_read_b128 v[122:125], v229 offset:32
	ds_read_b128 v[126:129], v229
	s_waitcnt lgkmcnt(3)
	v_pk_mul_f32 v[62:63], v[62:63], v[114:115]
	s_waitcnt lgkmcnt(2)
	v_pk_mul_f32 v[58:59], v[58:59], v[118:119]
	s_waitcnt lgkmcnt(1)
	v_pk_mul_f32 v[54:55], v[54:55], v[122:123]
	v_pk_mul_f32 v[64:65], v[64:65], v[116:117]
	v_pk_mul_f32 v[60:61], v[60:61], v[120:121]
	v_pk_mul_f32 v[56:57], v[56:57], v[124:125]
	s_waitcnt lgkmcnt(0)
	v_pk_mul_f32 v[52:53], v[52:53], v[128:129]
	v_pk_mul_f32 v[50:51], v[50:51], v[126:127]
	v_pk_mul_f32 v[46:47], v[46:47], v[114:115]
	v_pk_mul_f32 v[42:43], v[42:43], v[118:119]
	v_pk_mul_f32 v[38:39], v[38:39], v[122:123]
	v_pk_mul_f32 v[48:49], v[48:49], v[116:117]
	v_pk_mul_f32 v[44:45], v[44:45], v[120:121]
	v_pk_mul_f32 v[40:41], v[40:41], v[124:125]
	v_pk_mul_f32 v[36:37], v[36:37], v[128:129]
	v_pk_mul_f32 v[34:35], v[34:35], v[126:127]
	v_pk_mul_f32 v[30:31], v[30:31], v[114:115]
	v_pk_mul_f32 v[26:27], v[26:27], v[118:119]
	v_pk_mul_f32 v[22:23], v[22:23], v[122:123]
	v_pk_mul_f32 v[32:33], v[32:33], v[116:117]
	v_pk_mul_f32 v[28:29], v[28:29], v[120:121]
	v_pk_mul_f32 v[24:25], v[24:25], v[124:125]
	v_pk_mul_f32 v[20:21], v[20:21], v[128:129]
	v_pk_mul_f32 v[18:19], v[18:19], v[126:127]
	v_pk_mul_f32 v[14:15], v[14:15], v[114:115]
	v_pk_mul_f32 v[10:11], v[10:11], v[118:119]
	v_pk_mul_f32 v[6:7], v[6:7], v[122:123]
	v_pk_mul_f32 v[16:17], v[16:17], v[116:117]
	v_pk_mul_f32 v[12:13], v[12:13], v[120:121]
	v_pk_mul_f32 v[8:9], v[8:9], v[124:125]
	v_pk_mul_f32 v[4:5], v[4:5], v[128:129]
	v_pk_mul_f32 v[2:3], v[2:3], v[126:127]

.LBB0_1079:
	s_lshl_b32 s40, s2, 1
	v_add_u32_e32 v216, s40, v242
	ds_read_b64_tr_b16 v[210:211], v216 offset:24576
	ds_read_b64_tr_b16 v[212:213], v216 offset:25088
	v_mfma_f32_32x32x16_bf16 v[130:145], v[206:209], v[174:177], v[66:81]
	v_add_f32_e32 v114, v98, v99
	v_add_f32_e32 v114, v100, v114
	v_add_f32_e32 v114, v101, v114
	v_add_f32_e32 v114, v102, v114
	v_add_f32_e32 v114, v103, v114
	v_cvt_pk_bf16_f32 v166, v98, v99
	v_cvt_pk_bf16_f32 v167, v100, v101
	ds_read_b64_tr_b16 v[206:207], v216 offset:28672
	ds_read_b64_tr_b16 v[208:209], v216 offset:29184
	v_add_f32_e32 v98, v104, v114
	v_mfma_f32_32x32x16_bf16 v[114:129], v[198:201], v[174:177], v[66:81]
	v_add_f32_e32 v98, v105, v98
	v_add_f32_e32 v98, v106, v98
	v_add_f32_e32 v154, v107, v98
	v_cvt_pk_bf16_f32 v168, v102, v103
	v_cvt_pk_bf16_f32 v169, v104, v105
	ds_read_b64_tr_b16 v[98:99], v216 offset:25600
	ds_read_b64_tr_b16 v[100:101], v216 offset:26112
	v_mfma_f32_32x32x16_bf16 v[130:145], v[202:205], v[170:173], v[130:145]
	v_add_f32_e32 v102, v108, v154
	v_add_f32_e32 v102, v109, v102
	v_add_f32_e32 v102, v110, v102
	v_add_f32_e32 v154, v111, v102
	v_cvt_pk_bf16_f32 v162, v106, v107
	v_cvt_pk_bf16_f32 v163, v108, v109
	ds_read_b64_tr_b16 v[102:103], v216 offset:29696
	ds_read_b64_tr_b16 v[104:105], v216 offset:30208
	v_mfma_f32_32x32x16_bf16 v[114:129], v[194:197], v[170:173], v[114:129]
	v_add_f32_e32 v106, v112, v154
	v_add_f32_e32 v106, v113, v106
	v_add_f32_e32 v106, v82, v106
	v_add_f32_e32 v154, v83, v106
	v_cvt_pk_bf16_f32 v164, v110, v111
	v_cvt_pk_bf16_f32 v165, v112, v113
	ds_read_b64_tr_b16 v[106:107], v216 offset:26624
	ds_read_b64_tr_b16 v[108:109], v216 offset:27136
	v_mfma_f32_32x32x16_bf16 v[130:145], v[190:193], v[150:153], v[130:145]
	v_add_f32_e32 v110, v84, v154
	v_add_f32_e32 v110, v85, v110
	v_add_f32_e32 v110, v86, v110
	v_add_f32_e32 v154, v87, v110
	v_cvt_pk_bf16_f32 v158, v82, v83
	v_cvt_pk_bf16_f32 v159, v84, v85
	ds_read_b64_tr_b16 v[110:111], v216 offset:30720
	ds_read_b64_tr_b16 v[112:113], v216 offset:31232
	v_mfma_f32_32x32x16_bf16 v[114:129], v[186:189], v[150:153], v[114:129]
	v_add_f32_e32 v82, v88, v154
	v_add_f32_e32 v82, v89, v82
	v_add_f32_e32 v82, v90, v82
	v_add_f32_e32 v82, v91, v82
	v_cvt_pk_bf16_f32 v160, v86, v87
	v_cvt_pk_bf16_f32 v161, v88, v89
	ds_read_b64_tr_b16 v[86:87], v216 offset:27648
	ds_read_b64_tr_b16 v[88:89], v216 offset:28160
	v_mfma_f32_32x32x16_bf16 v[130:145], v[182:185], v[146:149], v[130:145]
	v_add_f32_e32 v82, v92, v82
	v_add_f32_e32 v82, v93, v82
	v_add_f32_e32 v82, v94, v82
	v_add_f32_e32 v82, v95, v82
	v_cvt_pk_bf16_f32 v154, v90, v91
	v_cvt_pk_bf16_f32 v155, v92, v93
	ds_read_b64_tr_b16 v[90:91], v216 offset:31744
	ds_read_b64_tr_b16 v[92:93], v216 offset:32256
	v_mfma_f32_32x32x16_bf16 v[114:129], v[178:181], v[146:149], v[114:129]
	v_add_f32_e32 v82, v96, v82
	v_add_f32_e32 v82, v97, v82
	v_add_f32_e32 v230, v244, v82
	v_cvt_pk_bf16_f32 v156, v94, v95
	v_cvt_pk_bf16_f32 v157, v96, v97
	s_waitcnt lgkmcnt(8)
	v_mfma_f32_32x32x16_bf16 v[50:65], v[166:169], v[210:213], v[50:65]
	s_add_i32 m0, s48, s44
	s_lshl_b32 s2, s43, 1
	global_load_lds_dwordx4 v218, s[98:99]
	s_add_u32 s98, s98, 0x10000
	s_addc_u32 s99, s99, 0
	v_mfma_f32_32x32x16_bf16 v[34:49], v[166:169], v[206:209], v[34:49]
	v_mfma_f32_32x32x16_bf16 v[50:65], v[162:165], v[98:101], v[50:65]
	v_max_f32_e32 v82, v130, v131
	v_max3_f32 v83, v132, v133, v115
	v_max3_f32 v82, v82, v114, v116
	v_max3_f32 v82, v82, v117, v134
	v_max3_f32 v83, v83, v136, v137
	v_max3_f32 v82, v82, v135, v118
	v_max3_f32 v83, v83, v120, v121
	v_max3_f32 v82, v82, v119, v138
	v_mfma_f32_32x32x16_bf16 v[34:49], v[162:165], v[102:105], v[34:49]
	v_max3_f32 v83, v83, v140, v141
	v_max3_f32 v82, v82, v139, v122
	v_max3_f32 v83, v83, v124, v125
	v_max3_f32 v82, v82, v123, v142
	v_max3_f32 v83, v83, v144, v145
	v_max3_f32 v82, v82, v143, v126
	v_max3_f32 v83, v83, v128, v129
	v_max3_f32 v82, v82, v127, v83
	v_mov_b32_e32 v83, v82
	v_add_u32_e32 v94, s43, v241
	v_add_u32_e32 v102, s40, v228
	v_permlane32_swap_b32_e32 v82, v83
	v_max_f32_e32 v82, v82, v83
	v_cmp_lt_f32_e32 vcc, s15, v82
	s_cbranch_vccnz .LBB0_1087
.LBB0_1080:
	ds_read_b128 v[82:85], v94
	ds_read_b128 v[198:201], v94 offset:512
	ds_read_b128 v[202:205], v94 offset:2048
	ds_read_b128 v[194:197], v94 offset:2560
	s_waitcnt lgkmcnt(4)
	v_mfma_f32_32x32x16_bf16 v[50:65], v[158:161], v[106:109], v[50:65]
	v_exp_f32_e32 v130, v130
	v_exp_f32_e32 v131, v131
	v_exp_f32_e32 v132, v132
	ds_read_b128 v[190:193], v94 offset:4096
	ds_read_b128 v[186:189], v94 offset:4608
	ds_read_b128 v[182:185], v94 offset:6144
	ds_read_b128 v[178:181], v94 offset:6656
	ds_read_b64_tr_b16 v[98:99],v102 offset:3072
	ds_read_b64_tr_b16 v[100:101],v102 offset:3584
	ds_read_b64_tr_b16 v[94:95],v102 offset:2048
	ds_read_b64_tr_b16 v[96:97],v102 offset:2560
	v_mfma_f32_32x32x16_bf16 v[34:49], v[158:161], v[110:113], v[34:49]
	s_add_i32 m0, s2, s45
	v_exp_f32_e32 v133, v133
	v_exp_f32_e32 v134, v134
	v_exp_f32_e32 v135, v135
	global_load_lds_dwordx4 v219, s[100:101]
	v_mfma_f32_32x32x16_bf16 v[50:65], v[154:157], v[86:89], v[50:65]
	v_exp_f32_e32 v136, v136
	v_exp_f32_e32 v137, v137
	v_exp_f32_e32 v138, v138
	ds_read_b64_tr_b16 v[86:87],v102 offset:0
	ds_read_b64_tr_b16 v[88:89],v102 offset:512
	v_mfma_f32_32x32x16_bf16 v[34:49], v[154:157], v[90:93], v[34:49]
	v_exp_f32_e32 v139, v139
	v_exp_f32_e32 v140, v140
	v_exp_f32_e32 v141, v141
	ds_read_b64_tr_b16 v[90:91],v102 offset:1024
	ds_read_b64_tr_b16 v[92:93],v102 offset:1536
	s_waitcnt lgkmcnt(6)
	v_mfma_f32_32x32x16_bf16 v[18:33], v[154:157], v[98:101], v[18:33]
	v_exp_f32_e32 v142, v142
	v_exp_f32_e32 v143, v143
	v_exp_f32_e32 v144, v144
	ds_read_b64_tr_b16 v[98:99],v102 offset:7168
	ds_read_b64_tr_b16 v[100:101],v102 offset:7680
	s_waitcnt lgkmcnt(6)
	v_mfma_f32_32x32x16_bf16 v[18:33], v[158:161], v[94:97], v[18:33]
	s_addk_i32 m0, 0x1f80
	v_exp_f32_e32 v145, v145
	v_exp_f32_e32 v114, v114
	v_exp_f32_e32 v115, v115
	ds_read_b64_tr_b16 v[94:95],v102 offset:6144
	ds_read_b64_tr_b16 v[96:97],v102 offset:6656
	global_load_lds_dwordx4 v219, s[100:101] offset:128
	s_add_u32 s100, s100, 0x10000
	s_addc_u32 s101, s101, 0
	s_waitcnt lgkmcnt(6)
	v_mfma_f32_32x32x16_bf16 v[18:33], v[166:169], v[86:89], v[18:33]
	v_exp_f32_e32 v116, v116
	v_exp_f32_e32 v117, v117
	v_exp_f32_e32 v118, v118
	ds_read_b64_tr_b16 v[86:87],v102 offset:4096
	ds_read_b64_tr_b16 v[88:89],v102 offset:4608
	s_waitcnt lgkmcnt(6)
	v_mfma_f32_32x32x16_bf16 v[18:33], v[162:165], v[90:93], v[18:33]
	v_exp_f32_e32 v119, v119
	v_exp_f32_e32 v120, v120
	v_exp_f32_e32 v121, v121
	ds_read_b64_tr_b16 v[90:91],v102 offset:5120
	ds_read_b64_tr_b16 v[92:93],v102 offset:5632
	s_waitcnt lgkmcnt(6)
	v_mfma_f32_32x32x16_bf16 v[2:17], v[154:157], v[98:101], v[2:17]
	v_exp_f32_e32 v122, v122
	v_exp_f32_e32 v123, v123
	s_waitcnt vmcnt(3) lgkmcnt(0)
	s_barrier
	v_mfma_f32_32x32x16_bf16 v[2:17], v[158:161], v[94:97], v[2:17]
	v_exp_f32_e32 v124, v124
	v_exp_f32_e32 v125, v125
	v_mfma_f32_32x32x16_bf16 v[2:17], v[166:169], v[86:89], v[2:17]
	v_exp_f32_e32 v126, v126
	v_exp_f32_e32 v127, v127
	v_mfma_f32_32x32x16_bf16 v[2:17], v[162:165], v[90:93], v[2:17]
	v_exp_f32_e32 v128, v128
	v_exp_f32_e32 v129, v129
	s_cmp_eq_u32 s3, 0
	s_cbranch_scc1 .LBB0_1082
	s_waitcnt lgkmcnt(0)
	s_mov_b32 s3, 0
	v_add_u32_e32 v229, s39, v243
	ds_read_b128 v[86:89], v229 offset:96
	ds_read_b128 v[90:93], v229 offset:64
	ds_read_b128 v[94:97], v229 offset:32
	ds_read_b128 v[98:101], v229
	s_waitcnt lgkmcnt(3)
	v_pk_mul_f32 v[62:63], v[62:63], v[86:87]
	s_waitcnt lgkmcnt(2)
	v_pk_mul_f32 v[58:59], v[58:59], v[90:91]
	s_waitcnt lgkmcnt(1)
	v_pk_mul_f32 v[54:55], v[54:55], v[94:95]
	v_pk_mul_f32 v[64:65], v[64:65], v[88:89]
	v_pk_mul_f32 v[60:61], v[60:61], v[92:93]
	v_pk_mul_f32 v[56:57], v[56:57], v[96:97]
	s_waitcnt lgkmcnt(0)
	v_pk_mul_f32 v[52:53], v[52:53], v[100:101]
	v_pk_mul_f32 v[50:51], v[50:51], v[98:99]
	v_pk_mul_f32 v[46:47], v[46:47], v[86:87]
	v_pk_mul_f32 v[42:43], v[42:43], v[90:91]
	v_pk_mul_f32 v[38:39], v[38:39], v[94:95]
	v_pk_mul_f32 v[48:49], v[48:49], v[88:89]
	v_pk_mul_f32 v[44:45], v[44:45], v[92:93]
	v_pk_mul_f32 v[40:41], v[40:41], v[96:97]
	v_pk_mul_f32 v[36:37], v[36:37], v[100:101]
	v_pk_mul_f32 v[34:35], v[34:35], v[98:99]
	v_pk_mul_f32 v[30:31], v[30:31], v[86:87]
	v_pk_mul_f32 v[26:27], v[26:27], v[90:91]
	v_pk_mul_f32 v[22:23], v[22:23], v[94:95]
	v_pk_mul_f32 v[32:33], v[32:33], v[88:89]
	v_pk_mul_f32 v[28:29], v[28:29], v[92:93]
	v_pk_mul_f32 v[24:25], v[24:25], v[96:97]
	v_pk_mul_f32 v[20:21], v[20:21], v[100:101]
	v_pk_mul_f32 v[18:19], v[18:19], v[98:99]
	v_pk_mul_f32 v[14:15], v[14:15], v[86:87]
	v_pk_mul_f32 v[10:11], v[10:11], v[90:91]
	v_pk_mul_f32 v[6:7], v[6:7], v[94:95]
	v_pk_mul_f32 v[16:17], v[16:17], v[88:89]
	v_pk_mul_f32 v[12:13], v[12:13], v[92:93]
	v_pk_mul_f32 v[8:9], v[8:9], v[96:97]
	v_pk_mul_f32 v[4:5], v[4:5], v[100:101]
	v_pk_mul_f32 v[2:3], v[2:3], v[98:99]
.LBB0_1082:
	s_add_i32 s2, s43, 0x2000
	s_cmpk_lg_i32 s43, 0x4000
	s_cselect_b32 s40, s2, 0
	s_lshl_b32 s47, s48, 1
	v_add_u32_e32 v231, s47, v242
	ds_read_b64_tr_b16 v[210:211], v231 offset:24576
	ds_read_b64_tr_b16 v[212:213], v231 offset:25088
	v_mfma_f32_32x32x16_bf16 v[98:113], v[82:85], v[174:177], v[66:81]
	v_add_f32_e32 v86, v130, v131
	v_add_f32_e32 v86, v132, v86
	v_add_f32_e32 v86, v133, v86
	v_add_f32_e32 v86, v134, v86
	v_add_f32_e32 v86, v135, v86
	v_cvt_pk_bf16_f32 v166, v130, v131
	v_cvt_pk_bf16_f32 v167, v132, v133
	ds_read_b64_tr_b16 v[206:207], v231 offset:28672
	ds_read_b64_tr_b16 v[208:209], v231 offset:29184
	v_add_f32_e32 v82, v136, v86
	v_add_f32_e32 v82, v137, v82
	v_add_f32_e32 v82, v138, v82
	v_add_f32_e32 v154, v139, v82
	v_mfma_f32_32x32x16_bf16 v[82:97], v[198:201], v[174:177], v[66:81]
	v_cvt_pk_bf16_f32 v168, v134, v135
	v_cvt_pk_bf16_f32 v169, v136, v137
	ds_read_b64_tr_b16 v[130:131], v231 offset:25600
	ds_read_b64_tr_b16 v[132:133], v231 offset:26112
	v_mfma_f32_32x32x16_bf16 v[98:113], v[202:205], v[170:173], v[98:113]
	v_add_f32_e32 v134, v140, v154
	v_add_f32_e32 v134, v141, v134
	v_add_f32_e32 v134, v142, v134
	v_add_f32_e32 v154, v143, v134
	v_cvt_pk_bf16_f32 v162, v138, v139
	v_cvt_pk_bf16_f32 v163, v140, v141
	ds_read_b64_tr_b16 v[134:135], v231 offset:29696
	ds_read_b64_tr_b16 v[136:137], v231 offset:30208
	v_mfma_f32_32x32x16_bf16 v[82:97], v[194:197], v[170:173], v[82:97]
	v_add_f32_e32 v138, v144, v154
	v_add_f32_e32 v138, v145, v138
	v_add_f32_e32 v138, v114, v138
	v_add_f32_e32 v154, v115, v138
	v_cvt_pk_bf16_f32 v164, v142, v143
	v_cvt_pk_bf16_f32 v165, v144, v145
	ds_read_b64_tr_b16 v[138:139], v231 offset:26624
	ds_read_b64_tr_b16 v[140:141], v231 offset:27136
	v_mfma_f32_32x32x16_bf16 v[98:113], v[190:193], v[150:153], v[98:113]
	v_add_f32_e32 v142, v116, v154
	v_add_f32_e32 v142, v117, v142
	v_add_f32_e32 v142, v118, v142
	v_add_f32_e32 v142, v119, v142
	v_cvt_pk_bf16_f32 v158, v114, v115
	v_cvt_pk_bf16_f32 v159, v116, v117
	ds_read_b64_tr_b16 v[114:115], v231 offset:30720
	ds_read_b64_tr_b16 v[116:117], v231 offset:31232
	v_mfma_f32_32x32x16_bf16 v[82:97], v[186:189], v[150:153], v[82:97]
	v_add_f32_e32 v142, v120, v142
	v_add_f32_e32 v142, v121, v142
	v_add_f32_e32 v142, v122, v142
	v_add_f32_e32 v142, v123, v142
	v_cvt_pk_bf16_f32 v160, v118, v119
	v_cvt_pk_bf16_f32 v161, v120, v121
	ds_read_b64_tr_b16 v[118:119], v231 offset:27648
	ds_read_b64_tr_b16 v[120:121], v231 offset:28160
	v_mfma_f32_32x32x16_bf16 v[98:113], v[182:185], v[146:149], v[98:113]
	v_add_f32_e32 v142, v124, v142
	v_add_f32_e32 v142, v125, v142
	v_add_f32_e32 v142, v126, v142
	v_add_f32_e32 v142, v127, v142
	v_cvt_pk_bf16_f32 v154, v122, v123
	v_cvt_pk_bf16_f32 v155, v124, v125
	ds_read_b64_tr_b16 v[122:123], v231 offset:31744
	ds_read_b64_tr_b16 v[124:125], v231 offset:32256
	v_mfma_f32_32x32x16_bf16 v[82:97], v[178:181], v[146:149], v[82:97]
	v_add_f32_e32 v142, v128, v142
	v_add_f32_e32 v142, v129, v142
	v_cvt_pk_bf16_f32 v156, v126, v127
	v_cvt_pk_bf16_f32 v157, v128, v129
	s_waitcnt lgkmcnt(8)
	v_mfma_f32_32x32x16_bf16 v[50:65], v[166:169], v[210:213], v[50:65]
	s_add_i32 m0, s43, s44
	s_lshl_b32 s2, s40, 1
	global_load_lds_dwordx4 v218, s[98:99]
	s_add_u32 s98, s98, 0x10000
	s_addc_u32 s99, s99, 0
	v_mfma_f32_32x32x16_bf16 v[34:49], v[166:169], v[206:209], v[34:49]
	v_mfma_f32_32x32x16_bf16 v[50:65], v[162:165], v[130:133], v[50:65]
	v_max_f32_e32 v126, v98, v99
	v_max3_f32 v127, v100, v101, v83
	v_max3_f32 v126, v126, v82, v84
	v_max3_f32 v126, v126, v85, v102
	v_max3_f32 v127, v127, v104, v105
	v_max3_f32 v126, v126, v103, v86
	v_max3_f32 v127, v127, v88, v89
	v_max3_f32 v126, v126, v87, v106
	v_mfma_f32_32x32x16_bf16 v[34:49], v[162:165], v[134:137], v[34:49]
	v_max3_f32 v127, v127, v108, v109
	v_max3_f32 v126, v126, v107, v90
	v_max3_f32 v127, v127, v92, v93
	v_max3_f32 v126, v126, v91, v110
	v_max3_f32 v127, v127, v112, v113
	v_max3_f32 v126, v126, v111, v94
	v_max3_f32 v127, v127, v96, v97
	v_max3_f32 v126, v126, v95, v127
	v_mov_b32_e32 v127, v126
	v_add_f32_e32 v244, v230, v142
	v_add_u32_e32 v130, s47, v228
	v_permlane32_swap_b32_e32 v126, v127
	v_max_f32_e32 v126, v126, v127
	v_cmp_lt_f32_e32 vcc, s15, v126
	s_cbranch_vccnz .LBB0_1090
.LBB0_1083:
	v_add_u32_e32 v126, s40, v241
	ds_read_b128 v[206:209], v126
	ds_read_b128 v[198:201], v126 offset:512
	ds_read_b128 v[202:205], v126 offset:2048
	ds_read_b128 v[194:197], v126 offset:2560
	s_waitcnt lgkmcnt(4)
	v_mfma_f32_32x32x16_bf16 v[50:65], v[158:161], v[138:141], v[50:65]
	v_exp_f32_e32 v98, v98
	v_exp_f32_e32 v99, v99
	v_exp_f32_e32 v100, v100
	ds_read_b128 v[190:193], v126 offset:4096
	ds_read_b128 v[186:189], v126 offset:4608
	ds_read_b128 v[182:185], v126 offset:6144
	ds_read_b128 v[178:181], v126 offset:6656
	ds_read_b64_tr_b16 v[126:127],v130 offset:3072
	ds_read_b64_tr_b16 v[128:129],v130 offset:3584
	v_mfma_f32_32x32x16_bf16 v[34:49], v[158:161], v[114:117], v[34:49]
	s_add_i32 s36, s2, s45
	s_mov_b32 m0, s36
	v_exp_f32_e32 v101, v101
	v_exp_f32_e32 v102, v102
	v_exp_f32_e32 v103, v103
	ds_read_b64_tr_b16 v[114:115],v130 offset:0
	ds_read_b64_tr_b16 v[116:117],v130 offset:512
	global_load_lds_dwordx4 v219, s[100:101]
	v_mfma_f32_32x32x16_bf16 v[50:65], v[154:157], v[118:121], v[50:65]
	v_exp_f32_e32 v104, v104
	v_exp_f32_e32 v105, v105
	v_exp_f32_e32 v106, v106
	ds_read_b64_tr_b16 v[118:119],v130 offset:1024
	ds_read_b64_tr_b16 v[120:121],v130 offset:1536
	v_mfma_f32_32x32x16_bf16 v[34:49], v[154:157], v[122:125], v[34:49]
	v_exp_f32_e32 v107, v107
	v_exp_f32_e32 v108, v108
	v_exp_f32_e32 v109, v109
	ds_read_b64_tr_b16 v[122:123],v130 offset:2048
	ds_read_b64_tr_b16 v[124:125],v130 offset:2560
	s_waitcnt lgkmcnt(6)
	v_mfma_f32_32x32x16_bf16 v[18:33], v[154:157], v[126:129], v[18:33]
	v_exp_f32_e32 v110, v110
	v_exp_f32_e32 v111, v111
	v_exp_f32_e32 v112, v112
	ds_read_b64_tr_b16 v[126:127],v130 offset:7168
	ds_read_b64_tr_b16 v[128:129],v130 offset:7680
	s_waitcnt lgkmcnt(6)
	v_mfma_f32_32x32x16_bf16 v[18:33], v[166:169], v[114:117], v[18:33]
	s_add_i32 m0, s36, 0x1f80
	v_exp_f32_e32 v113, v113
	v_exp_f32_e32 v82, v82
	v_exp_f32_e32 v83, v83
	ds_read_b64_tr_b16 v[114:115],v130 offset:4096
	ds_read_b64_tr_b16 v[116:117],v130 offset:4608
	global_load_lds_dwordx4 v219, s[100:101] offset:128
	s_add_u32 s100, s100, 0x10000
	s_addc_u32 s101, s101, 0
	s_waitcnt lgkmcnt(6)
	v_mfma_f32_32x32x16_bf16 v[18:33], v[162:165], v[118:121], v[18:33]
	v_exp_f32_e32 v84, v84
	v_exp_f32_e32 v85, v85
	v_exp_f32_e32 v86, v86
	ds_read_b64_tr_b16 v[118:119],v130 offset:5120
	ds_read_b64_tr_b16 v[120:121],v130 offset:5632
	s_waitcnt lgkmcnt(6)
	v_mfma_f32_32x32x16_bf16 v[18:33], v[158:161], v[122:125], v[18:33]
	v_exp_f32_e32 v87, v87
	v_exp_f32_e32 v88, v88
	v_exp_f32_e32 v89, v89
	ds_read_b64_tr_b16 v[122:123],v130 offset:6144
	ds_read_b64_tr_b16 v[124:125],v130 offset:6656
	s_waitcnt lgkmcnt(6)
	v_mfma_f32_32x32x16_bf16 v[2:17], v[154:157], v[126:129], v[2:17]
	v_exp_f32_e32 v90, v90
	v_exp_f32_e32 v91, v91
	s_waitcnt vmcnt(3) lgkmcnt(0)
	s_barrier
	v_mfma_f32_32x32x16_bf16 v[2:17], v[166:169], v[114:117], v[2:17]
	v_exp_f32_e32 v92, v92
	v_exp_f32_e32 v93, v93
	v_mfma_f32_32x32x16_bf16 v[2:17], v[162:165], v[118:121], v[2:17]
	v_exp_f32_e32 v94, v94
	v_exp_f32_e32 v95, v95
	v_mfma_f32_32x32x16_bf16 v[2:17], v[158:161], v[122:125], v[2:17]
	v_exp_f32_e32 v96, v96
	v_exp_f32_e32 v97, v97
	s_cmp_eq_u32 s3, 0
	s_cbranch_scc1 .LBB0_1085
	s_waitcnt lgkmcnt(0)
	s_mov_b32 s3, 0
	v_add_u32_e32 v229, s39, v243
	ds_read_b128 v[114:117], v229 offset:96
	ds_read_b128 v[118:121], v229 offset:64
	ds_read_b128 v[122:125], v229 offset:32
	ds_read_b128 v[126:129], v229
	s_waitcnt lgkmcnt(3)
	v_pk_mul_f32 v[62:63], v[62:63], v[114:115]
	s_waitcnt lgkmcnt(2)
	v_pk_mul_f32 v[58:59], v[58:59], v[118:119]
	s_waitcnt lgkmcnt(1)
	v_pk_mul_f32 v[54:55], v[54:55], v[122:123]
	v_pk_mul_f32 v[64:65], v[64:65], v[116:117]
	v_pk_mul_f32 v[60:61], v[60:61], v[120:121]
	v_pk_mul_f32 v[56:57], v[56:57], v[124:125]
	s_waitcnt lgkmcnt(0)
	v_pk_mul_f32 v[52:53], v[52:53], v[128:129]
	v_pk_mul_f32 v[50:51], v[50:51], v[126:127]
	v_pk_mul_f32 v[46:47], v[46:47], v[114:115]
	v_pk_mul_f32 v[42:43], v[42:43], v[118:119]
	v_pk_mul_f32 v[38:39], v[38:39], v[122:123]
	v_pk_mul_f32 v[48:49], v[48:49], v[116:117]
	v_pk_mul_f32 v[44:45], v[44:45], v[120:121]
	v_pk_mul_f32 v[40:41], v[40:41], v[124:125]
	v_pk_mul_f32 v[36:37], v[36:37], v[128:129]
	v_pk_mul_f32 v[34:35], v[34:35], v[126:127]
	v_pk_mul_f32 v[30:31], v[30:31], v[114:115]
	v_pk_mul_f32 v[26:27], v[26:27], v[118:119]
	v_pk_mul_f32 v[22:23], v[22:23], v[122:123]
	v_pk_mul_f32 v[32:33], v[32:33], v[116:117]
	v_pk_mul_f32 v[28:29], v[28:29], v[120:121]
	v_pk_mul_f32 v[24:25], v[24:25], v[124:125]
	v_pk_mul_f32 v[20:21], v[20:21], v[128:129]
	v_pk_mul_f32 v[18:19], v[18:19], v[126:127]
	v_pk_mul_f32 v[14:15], v[14:15], v[114:115]
	v_pk_mul_f32 v[10:11], v[10:11], v[118:119]
	v_pk_mul_f32 v[6:7], v[6:7], v[122:123]
	v_pk_mul_f32 v[16:17], v[16:17], v[116:117]
	v_pk_mul_f32 v[12:13], v[12:13], v[120:121]
	v_pk_mul_f32 v[8:9], v[8:9], v[124:125]
	v_pk_mul_f32 v[4:5], v[4:5], v[128:129]
	v_pk_mul_f32 v[2:3], v[2:3], v[126:127]
